# residual epilogue: XN written as 16-byte pieces per lane (DPP quad exchange pairs adjacent column groups), half the store requests
# speedup vs baseline: 1.0095x; 1.0095x over previous
.Lrn_nors:
	s_waitcnt lgkmcnt(0)
	s_barrier
	v_add_u32_e32 v211, s62, v223
	v_lshlrev_b32_e32 v210, 2, v211
	v_add_u32_e32 v210, 0x22000, v210
	ds_read_b32 v182, v210 offset:0
	ds_read_b32 v184, v210 offset:64
	ds_read_b32 v186, v210 offset:128
	ds_read_b32 v188, v210 offset:192
	ds_read_b32 v190, v210 offset:512
	ds_read_b32 v192, v210 offset:576
	ds_read_b32 v194, v210 offset:640
	ds_read_b32 v196, v210 offset:704
	v_pk_add_f32 v[166:167], v[166:167], 1.0 op_sel_hi:[1,0]
	v_pk_mul_f32 v[134:135], v[134:135], v[166:167]
	v_pk_add_f32 v[168:169], v[168:169], 1.0 op_sel_hi:[1,0]
	v_pk_mul_f32 v[136:137], v[136:137], v[168:169]
	v_pk_add_f32 v[170:171], v[170:171], 1.0 op_sel_hi:[1,0]
	v_pk_mul_f32 v[138:139], v[138:139], v[170:171]
	v_pk_add_f32 v[172:173], v[172:173], 1.0 op_sel_hi:[1,0]
	v_pk_mul_f32 v[140:141], v[140:141], v[172:173]
	v_pk_add_f32 v[174:175], v[174:175], 1.0 op_sel_hi:[1,0]
	v_pk_mul_f32 v[142:143], v[142:143], v[174:175]
	v_pk_add_f32 v[176:177], v[176:177], 1.0 op_sel_hi:[1,0]
	v_pk_mul_f32 v[144:145], v[144:145], v[176:177]
	v_pk_add_f32 v[178:179], v[178:179], 1.0 op_sel_hi:[1,0]
	v_pk_mul_f32 v[146:147], v[146:147], v[178:179]
	v_pk_add_f32 v[180:181], v[180:181], 1.0 op_sel_hi:[1,0]
	v_pk_mul_f32 v[148:149], v[148:149], v[180:181]
	v_lshl_add_u64 v[242:243], s[10:11], 0, v[226:227]
	v_lshl_add_u64 v[242:243], v[242:243], 0, v[228:229]
	v_readlane_b32 s36, v253, 42
	v_readlane_b32 s37, v253, 43
	s_add_u32 s36, s36, 0x7400000
	s_addc_u32 s37, s37, 0
	v_lshrrev_b64 v[244:245], 1, v[226:227]
	v_lshrrev_b64 v[246:247], 1, v[228:229]
	v_lshl_add_u64 v[244:245], s[36:37], 0, v[244:245]
	v_lshl_add_u64 v[244:245], v[244:245], 0, v[246:247]
	s_mov_b32 s31, 0
	s_waitcnt lgkmcnt(0)
	s_cmp_eq_u32 s38, 7
	s_cbranch_scc1 .Lrn_final_out
	v_mbcnt_lo_u32_b32 v246, -1, 0
	v_mbcnt_hi_u32_b32 v246, -1, v246
	v_and_b32_e32 v246, 3, v246
	v_lshlrev_b32_e32 v246, 3, v246
	v_mov_b32_e32 v247, 0
	v_lshl_add_u64 v[244:245], v[244:245], 0, v[246:247]
	s_mov_b32 vcc_lo, 0x33333333
	s_mov_b32 vcc_hi, 0x33333333
	s_mov_b32 s30, 0x0
	v_lshl_add_u64 v[248:249], v[244:245], 0, s[30:31]
	v_pk_mul_f32 v[198:199], v[130:131], v[182:183] op_sel_hi:[1,0]
	v_pk_fma_f32 v[198:199], v[198:199], v[134:135], v[150:151]
	v_pk_mul_f32 v[200:201], v[132:133], v[182:183] op_sel_hi:[1,0]
	v_pk_fma_f32 v[200:201], v[200:201], v[136:137], v[152:153]
	v_cvt_pk_bf16_f32 v202, v198, v199
	v_cvt_pk_bf16_f32 v203, v200, v201
	v_pk_mul_f32 v[198:199], v[126:127], v[182:183] op_sel_hi:[1,0]
	v_pk_fma_f32 v[198:199], v[198:199], v[138:139], v[154:155]
	v_pk_mul_f32 v[200:201], v[128:129], v[182:183] op_sel_hi:[1,0]
	v_pk_fma_f32 v[200:201], v[200:201], v[140:141], v[156:157]
	v_cvt_pk_bf16_f32 v204, v198, v199
	v_cvt_pk_bf16_f32 v205, v200, v201
	v_mov_b32_dpp v214, v202 quad_perm:[0,2,0,2] row_mask:0xf bank_mask:0xf
	v_mov_b32_dpp v215, v203 quad_perm:[0,2,0,2] row_mask:0xf bank_mask:0xf
	v_mov_b32_dpp v216, v202 quad_perm:[1,3,1,3] row_mask:0xf bank_mask:0xf
	v_mov_b32_dpp v217, v203 quad_perm:[1,3,1,3] row_mask:0xf bank_mask:0xf
	v_cndmask_b32_dpp v214, v204, v214, vcc quad_perm:[0,2,0,2] row_mask:0xf bank_mask:0xf
	v_cndmask_b32_dpp v215, v205, v215, vcc quad_perm:[0,2,0,2] row_mask:0xf bank_mask:0xf
	v_cndmask_b32_dpp v216, v204, v216, vcc quad_perm:[1,3,1,3] row_mask:0xf bank_mask:0xf
	v_cndmask_b32_dpp v217, v205, v217, vcc quad_perm:[1,3,1,3] row_mask:0xf bank_mask:0xf
	global_store_dwordx4 v[248:249], v[214:217], off offset:0
	v_pk_mul_f32 v[198:199], v[122:123], v[182:183] op_sel_hi:[1,0]
	v_pk_fma_f32 v[198:199], v[198:199], v[142:143], v[158:159]
	v_pk_mul_f32 v[200:201], v[124:125], v[182:183] op_sel_hi:[1,0]
	v_pk_fma_f32 v[200:201], v[200:201], v[144:145], v[160:161]
	v_cvt_pk_bf16_f32 v202, v198, v199
	v_cvt_pk_bf16_f32 v203, v200, v201
	v_pk_mul_f32 v[198:199], v[118:119], v[182:183] op_sel_hi:[1,0]
	v_pk_fma_f32 v[198:199], v[198:199], v[146:147], v[162:163]
	v_pk_mul_f32 v[200:201], v[120:121], v[182:183] op_sel_hi:[1,0]
	v_pk_fma_f32 v[200:201], v[200:201], v[148:149], v[164:165]
	v_cvt_pk_bf16_f32 v204, v198, v199
	v_cvt_pk_bf16_f32 v205, v200, v201
	v_mov_b32_dpp v214, v202 quad_perm:[0,2,0,2] row_mask:0xf bank_mask:0xf
	v_mov_b32_dpp v215, v203 quad_perm:[0,2,0,2] row_mask:0xf bank_mask:0xf
	v_mov_b32_dpp v216, v202 quad_perm:[1,3,1,3] row_mask:0xf bank_mask:0xf
	v_mov_b32_dpp v217, v203 quad_perm:[1,3,1,3] row_mask:0xf bank_mask:0xf
	v_cndmask_b32_dpp v214, v204, v214, vcc quad_perm:[0,2,0,2] row_mask:0xf bank_mask:0xf
	v_cndmask_b32_dpp v215, v205, v215, vcc quad_perm:[0,2,0,2] row_mask:0xf bank_mask:0xf
	v_cndmask_b32_dpp v216, v204, v216, vcc quad_perm:[1,3,1,3] row_mask:0xf bank_mask:0xf
	v_cndmask_b32_dpp v217, v205, v217, vcc quad_perm:[1,3,1,3] row_mask:0xf bank_mask:0xf
	global_store_dwordx4 v[248:249], v[214:217], off offset:256
	s_mov_b32 s30, 0x8000
	v_lshl_add_u64 v[248:249], v[244:245], 0, s[30:31]
	v_pk_mul_f32 v[198:199], v[114:115], v[184:185] op_sel_hi:[1,0]
	v_pk_fma_f32 v[198:199], v[198:199], v[134:135], v[150:151]
	v_pk_mul_f32 v[200:201], v[116:117], v[184:185] op_sel_hi:[1,0]
	v_pk_fma_f32 v[200:201], v[200:201], v[136:137], v[152:153]
	v_cvt_pk_bf16_f32 v202, v198, v199
	v_cvt_pk_bf16_f32 v203, v200, v201
	v_pk_mul_f32 v[198:199], v[110:111], v[184:185] op_sel_hi:[1,0]
	v_pk_fma_f32 v[198:199], v[198:199], v[138:139], v[154:155]
	v_pk_mul_f32 v[200:201], v[112:113], v[184:185] op_sel_hi:[1,0]
	v_pk_fma_f32 v[200:201], v[200:201], v[140:141], v[156:157]
	v_cvt_pk_bf16_f32 v204, v198, v199
	v_cvt_pk_bf16_f32 v205, v200, v201
	v_mov_b32_dpp v214, v202 quad_perm:[0,2,0,2] row_mask:0xf bank_mask:0xf
	v_mov_b32_dpp v215, v203 quad_perm:[0,2,0,2] row_mask:0xf bank_mask:0xf
	v_mov_b32_dpp v216, v202 quad_perm:[1,3,1,3] row_mask:0xf bank_mask:0xf
	v_mov_b32_dpp v217, v203 quad_perm:[1,3,1,3] row_mask:0xf bank_mask:0xf
	v_cndmask_b32_dpp v214, v204, v214, vcc quad_perm:[0,2,0,2] row_mask:0xf bank_mask:0xf
	v_cndmask_b32_dpp v215, v205, v215, vcc quad_perm:[0,2,0,2] row_mask:0xf bank_mask:0xf
	v_cndmask_b32_dpp v216, v204, v216, vcc quad_perm:[1,3,1,3] row_mask:0xf bank_mask:0xf
	v_cndmask_b32_dpp v217, v205, v217, vcc quad_perm:[1,3,1,3] row_mask:0xf bank_mask:0xf
	global_store_dwordx4 v[248:249], v[214:217], off offset:0
	v_pk_mul_f32 v[198:199], v[106:107], v[184:185] op_sel_hi:[1,0]
	v_pk_fma_f32 v[198:199], v[198:199], v[142:143], v[158:159]
	v_pk_mul_f32 v[200:201], v[108:109], v[184:185] op_sel_hi:[1,0]
	v_pk_fma_f32 v[200:201], v[200:201], v[144:145], v[160:161]
	v_cvt_pk_bf16_f32 v202, v198, v199
	v_cvt_pk_bf16_f32 v203, v200, v201
	v_pk_mul_f32 v[198:199], v[102:103], v[184:185] op_sel_hi:[1,0]
	v_pk_fma_f32 v[198:199], v[198:199], v[146:147], v[162:163]
	v_pk_mul_f32 v[200:201], v[104:105], v[184:185] op_sel_hi:[1,0]
	v_pk_fma_f32 v[200:201], v[200:201], v[148:149], v[164:165]
	v_cvt_pk_bf16_f32 v204, v198, v199
	v_cvt_pk_bf16_f32 v205, v200, v201
	v_mov_b32_dpp v214, v202 quad_perm:[0,2,0,2] row_mask:0xf bank_mask:0xf
	v_mov_b32_dpp v215, v203 quad_perm:[0,2,0,2] row_mask:0xf bank_mask:0xf
	v_mov_b32_dpp v216, v202 quad_perm:[1,3,1,3] row_mask:0xf bank_mask:0xf
	v_mov_b32_dpp v217, v203 quad_perm:[1,3,1,3] row_mask:0xf bank_mask:0xf
	v_cndmask_b32_dpp v214, v204, v214, vcc quad_perm:[0,2,0,2] row_mask:0xf bank_mask:0xf
	v_cndmask_b32_dpp v215, v205, v215, vcc quad_perm:[0,2,0,2] row_mask:0xf bank_mask:0xf
	v_cndmask_b32_dpp v216, v204, v216, vcc quad_perm:[1,3,1,3] row_mask:0xf bank_mask:0xf
	v_cndmask_b32_dpp v217, v205, v217, vcc quad_perm:[1,3,1,3] row_mask:0xf bank_mask:0xf
	global_store_dwordx4 v[248:249], v[214:217], off offset:256
	s_mov_b32 s30, 0x10000
	v_lshl_add_u64 v[248:249], v[244:245], 0, s[30:31]
	v_pk_mul_f32 v[198:199], v[98:99], v[186:187] op_sel_hi:[1,0]
	v_pk_fma_f32 v[198:199], v[198:199], v[134:135], v[150:151]
	v_pk_mul_f32 v[200:201], v[100:101], v[186:187] op_sel_hi:[1,0]
	v_pk_fma_f32 v[200:201], v[200:201], v[136:137], v[152:153]
	v_cvt_pk_bf16_f32 v202, v198, v199
	v_cvt_pk_bf16_f32 v203, v200, v201
	v_pk_mul_f32 v[198:199], v[94:95], v[186:187] op_sel_hi:[1,0]
	v_pk_fma_f32 v[198:199], v[198:199], v[138:139], v[154:155]
	v_pk_mul_f32 v[200:201], v[96:97], v[186:187] op_sel_hi:[1,0]
	v_pk_fma_f32 v[200:201], v[200:201], v[140:141], v[156:157]
	v_cvt_pk_bf16_f32 v204, v198, v199
	v_cvt_pk_bf16_f32 v205, v200, v201
	v_mov_b32_dpp v214, v202 quad_perm:[0,2,0,2] row_mask:0xf bank_mask:0xf
	v_mov_b32_dpp v215, v203 quad_perm:[0,2,0,2] row_mask:0xf bank_mask:0xf
	v_mov_b32_dpp v216, v202 quad_perm:[1,3,1,3] row_mask:0xf bank_mask:0xf
	v_mov_b32_dpp v217, v203 quad_perm:[1,3,1,3] row_mask:0xf bank_mask:0xf
	v_cndmask_b32_dpp v214, v204, v214, vcc quad_perm:[0,2,0,2] row_mask:0xf bank_mask:0xf
	v_cndmask_b32_dpp v215, v205, v215, vcc quad_perm:[0,2,0,2] row_mask:0xf bank_mask:0xf
	v_cndmask_b32_dpp v216, v204, v216, vcc quad_perm:[1,3,1,3] row_mask:0xf bank_mask:0xf
	v_cndmask_b32_dpp v217, v205, v217, vcc quad_perm:[1,3,1,3] row_mask:0xf bank_mask:0xf
	global_store_dwordx4 v[248:249], v[214:217], off offset:0
	v_pk_mul_f32 v[198:199], v[90:91], v[186:187] op_sel_hi:[1,0]
	v_pk_fma_f32 v[198:199], v[198:199], v[142:143], v[158:159]
	v_pk_mul_f32 v[200:201], v[92:93], v[186:187] op_sel_hi:[1,0]
	v_pk_fma_f32 v[200:201], v[200:201], v[144:145], v[160:161]
	v_cvt_pk_bf16_f32 v202, v198, v199
	v_cvt_pk_bf16_f32 v203, v200, v201
	v_pk_mul_f32 v[198:199], v[86:87], v[186:187] op_sel_hi:[1,0]
	v_pk_fma_f32 v[198:199], v[198:199], v[146:147], v[162:163]
	v_pk_mul_f32 v[200:201], v[88:89], v[186:187] op_sel_hi:[1,0]
	v_pk_fma_f32 v[200:201], v[200:201], v[148:149], v[164:165]
	v_cvt_pk_bf16_f32 v204, v198, v199
	v_cvt_pk_bf16_f32 v205, v200, v201
	v_mov_b32_dpp v214, v202 quad_perm:[0,2,0,2] row_mask:0xf bank_mask:0xf
	v_mov_b32_dpp v215, v203 quad_perm:[0,2,0,2] row_mask:0xf bank_mask:0xf
	v_mov_b32_dpp v216, v202 quad_perm:[1,3,1,3] row_mask:0xf bank_mask:0xf
	v_mov_b32_dpp v217, v203 quad_perm:[1,3,1,3] row_mask:0xf bank_mask:0xf
	v_cndmask_b32_dpp v214, v204, v214, vcc quad_perm:[0,2,0,2] row_mask:0xf bank_mask:0xf
	v_cndmask_b32_dpp v215, v205, v215, vcc quad_perm:[0,2,0,2] row_mask:0xf bank_mask:0xf
	v_cndmask_b32_dpp v216, v204, v216, vcc quad_perm:[1,3,1,3] row_mask:0xf bank_mask:0xf
	v_cndmask_b32_dpp v217, v205, v217, vcc quad_perm:[1,3,1,3] row_mask:0xf bank_mask:0xf
	global_store_dwordx4 v[248:249], v[214:217], off offset:256
	s_mov_b32 s30, 0x18000
	v_lshl_add_u64 v[248:249], v[244:245], 0, s[30:31]
	v_pk_mul_f32 v[198:199], v[82:83], v[188:189] op_sel_hi:[1,0]
	v_pk_fma_f32 v[198:199], v[198:199], v[134:135], v[150:151]
	v_pk_mul_f32 v[200:201], v[84:85], v[188:189] op_sel_hi:[1,0]
	v_pk_fma_f32 v[200:201], v[200:201], v[136:137], v[152:153]
	v_cvt_pk_bf16_f32 v202, v198, v199
	v_cvt_pk_bf16_f32 v203, v200, v201
	v_pk_mul_f32 v[198:199], v[78:79], v[188:189] op_sel_hi:[1,0]
	v_pk_fma_f32 v[198:199], v[198:199], v[138:139], v[154:155]
	v_pk_mul_f32 v[200:201], v[80:81], v[188:189] op_sel_hi:[1,0]
	v_pk_fma_f32 v[200:201], v[200:201], v[140:141], v[156:157]
	v_cvt_pk_bf16_f32 v204, v198, v199
	v_cvt_pk_bf16_f32 v205, v200, v201
	v_mov_b32_dpp v214, v202 quad_perm:[0,2,0,2] row_mask:0xf bank_mask:0xf
	v_mov_b32_dpp v215, v203 quad_perm:[0,2,0,2] row_mask:0xf bank_mask:0xf
	v_mov_b32_dpp v216, v202 quad_perm:[1,3,1,3] row_mask:0xf bank_mask:0xf
	v_mov_b32_dpp v217, v203 quad_perm:[1,3,1,3] row_mask:0xf bank_mask:0xf
	v_cndmask_b32_dpp v214, v204, v214, vcc quad_perm:[0,2,0,2] row_mask:0xf bank_mask:0xf
	v_cndmask_b32_dpp v215, v205, v215, vcc quad_perm:[0,2,0,2] row_mask:0xf bank_mask:0xf
	v_cndmask_b32_dpp v216, v204, v216, vcc quad_perm:[1,3,1,3] row_mask:0xf bank_mask:0xf
	v_cndmask_b32_dpp v217, v205, v217, vcc quad_perm:[1,3,1,3] row_mask:0xf bank_mask:0xf
	global_store_dwordx4 v[248:249], v[214:217], off offset:0
	v_pk_mul_f32 v[198:199], v[74:75], v[188:189] op_sel_hi:[1,0]
	v_pk_fma_f32 v[198:199], v[198:199], v[142:143], v[158:159]
	v_pk_mul_f32 v[200:201], v[76:77], v[188:189] op_sel_hi:[1,0]
	v_pk_fma_f32 v[200:201], v[200:201], v[144:145], v[160:161]
	v_cvt_pk_bf16_f32 v202, v198, v199
	v_cvt_pk_bf16_f32 v203, v200, v201
	v_pk_mul_f32 v[198:199], v[70:71], v[188:189] op_sel_hi:[1,0]
	v_pk_fma_f32 v[198:199], v[198:199], v[146:147], v[162:163]
	v_pk_mul_f32 v[200:201], v[72:73], v[188:189] op_sel_hi:[1,0]
	v_pk_fma_f32 v[200:201], v[200:201], v[148:149], v[164:165]
	v_cvt_pk_bf16_f32 v204, v198, v199
	v_cvt_pk_bf16_f32 v205, v200, v201
	v_mov_b32_dpp v214, v202 quad_perm:[0,2,0,2] row_mask:0xf bank_mask:0xf
	v_mov_b32_dpp v215, v203 quad_perm:[0,2,0,2] row_mask:0xf bank_mask:0xf
	v_mov_b32_dpp v216, v202 quad_perm:[1,3,1,3] row_mask:0xf bank_mask:0xf
	v_mov_b32_dpp v217, v203 quad_perm:[1,3,1,3] row_mask:0xf bank_mask:0xf
	v_cndmask_b32_dpp v214, v204, v214, vcc quad_perm:[0,2,0,2] row_mask:0xf bank_mask:0xf
	v_cndmask_b32_dpp v215, v205, v215, vcc quad_perm:[0,2,0,2] row_mask:0xf bank_mask:0xf
	v_cndmask_b32_dpp v216, v204, v216, vcc quad_perm:[1,3,1,3] row_mask:0xf bank_mask:0xf
	v_cndmask_b32_dpp v217, v205, v217, vcc quad_perm:[1,3,1,3] row_mask:0xf bank_mask:0xf
	global_store_dwordx4 v[248:249], v[214:217], off offset:256
	s_mov_b32 s30, 0x40000
	v_lshl_add_u64 v[248:249], v[244:245], 0, s[30:31]
	v_pk_mul_f32 v[198:199], v[66:67], v[190:191] op_sel_hi:[1,0]
	v_pk_fma_f32 v[198:199], v[198:199], v[134:135], v[150:151]
	v_pk_mul_f32 v[200:201], v[68:69], v[190:191] op_sel_hi:[1,0]
	v_pk_fma_f32 v[200:201], v[200:201], v[136:137], v[152:153]
	v_cvt_pk_bf16_f32 v202, v198, v199
	v_cvt_pk_bf16_f32 v203, v200, v201
	v_pk_mul_f32 v[198:199], v[62:63], v[190:191] op_sel_hi:[1,0]
	v_pk_fma_f32 v[198:199], v[198:199], v[138:139], v[154:155]
	v_pk_mul_f32 v[200:201], v[64:65], v[190:191] op_sel_hi:[1,0]
	v_pk_fma_f32 v[200:201], v[200:201], v[140:141], v[156:157]
	v_cvt_pk_bf16_f32 v204, v198, v199
	v_cvt_pk_bf16_f32 v205, v200, v201
	v_mov_b32_dpp v214, v202 quad_perm:[0,2,0,2] row_mask:0xf bank_mask:0xf
	v_mov_b32_dpp v215, v203 quad_perm:[0,2,0,2] row_mask:0xf bank_mask:0xf
	v_mov_b32_dpp v216, v202 quad_perm:[1,3,1,3] row_mask:0xf bank_mask:0xf
	v_mov_b32_dpp v217, v203 quad_perm:[1,3,1,3] row_mask:0xf bank_mask:0xf
	v_cndmask_b32_dpp v214, v204, v214, vcc quad_perm:[0,2,0,2] row_mask:0xf bank_mask:0xf
	v_cndmask_b32_dpp v215, v205, v215, vcc quad_perm:[0,2,0,2] row_mask:0xf bank_mask:0xf
	v_cndmask_b32_dpp v216, v204, v216, vcc quad_perm:[1,3,1,3] row_mask:0xf bank_mask:0xf
	v_cndmask_b32_dpp v217, v205, v217, vcc quad_perm:[1,3,1,3] row_mask:0xf bank_mask:0xf
	global_store_dwordx4 v[248:249], v[214:217], off offset:0
	v_pk_mul_f32 v[198:199], v[58:59], v[190:191] op_sel_hi:[1,0]
	v_pk_fma_f32 v[198:199], v[198:199], v[142:143], v[158:159]
	v_pk_mul_f32 v[200:201], v[60:61], v[190:191] op_sel_hi:[1,0]
	v_pk_fma_f32 v[200:201], v[200:201], v[144:145], v[160:161]
	v_cvt_pk_bf16_f32 v202, v198, v199
	v_cvt_pk_bf16_f32 v203, v200, v201
	v_pk_mul_f32 v[198:199], v[54:55], v[190:191] op_sel_hi:[1,0]
	v_pk_fma_f32 v[198:199], v[198:199], v[146:147], v[162:163]
	v_pk_mul_f32 v[200:201], v[56:57], v[190:191] op_sel_hi:[1,0]
	v_pk_fma_f32 v[200:201], v[200:201], v[148:149], v[164:165]
	v_cvt_pk_bf16_f32 v204, v198, v199
	v_cvt_pk_bf16_f32 v205, v200, v201
	v_mov_b32_dpp v214, v202 quad_perm:[0,2,0,2] row_mask:0xf bank_mask:0xf
	v_mov_b32_dpp v215, v203 quad_perm:[0,2,0,2] row_mask:0xf bank_mask:0xf
	v_mov_b32_dpp v216, v202 quad_perm:[1,3,1,3] row_mask:0xf bank_mask:0xf
	v_mov_b32_dpp v217, v203 quad_perm:[1,3,1,3] row_mask:0xf bank_mask:0xf
	v_cndmask_b32_dpp v214, v204, v214, vcc quad_perm:[0,2,0,2] row_mask:0xf bank_mask:0xf
	v_cndmask_b32_dpp v215, v205, v215, vcc quad_perm:[0,2,0,2] row_mask:0xf bank_mask:0xf
	v_cndmask_b32_dpp v216, v204, v216, vcc quad_perm:[1,3,1,3] row_mask:0xf bank_mask:0xf
	v_cndmask_b32_dpp v217, v205, v217, vcc quad_perm:[1,3,1,3] row_mask:0xf bank_mask:0xf
	global_store_dwordx4 v[248:249], v[214:217], off offset:256
	s_mov_b32 s30, 0x48000
	v_lshl_add_u64 v[248:249], v[244:245], 0, s[30:31]
	v_pk_mul_f32 v[198:199], v[50:51], v[192:193] op_sel_hi:[1,0]
	v_pk_fma_f32 v[198:199], v[198:199], v[134:135], v[150:151]
	v_pk_mul_f32 v[200:201], v[52:53], v[192:193] op_sel_hi:[1,0]
	v_pk_fma_f32 v[200:201], v[200:201], v[136:137], v[152:153]
	v_cvt_pk_bf16_f32 v202, v198, v199
	v_cvt_pk_bf16_f32 v203, v200, v201
	v_pk_mul_f32 v[198:199], v[46:47], v[192:193] op_sel_hi:[1,0]
	v_pk_fma_f32 v[198:199], v[198:199], v[138:139], v[154:155]
	v_pk_mul_f32 v[200:201], v[48:49], v[192:193] op_sel_hi:[1,0]
	v_pk_fma_f32 v[200:201], v[200:201], v[140:141], v[156:157]
	v_cvt_pk_bf16_f32 v204, v198, v199
	v_cvt_pk_bf16_f32 v205, v200, v201
	v_mov_b32_dpp v214, v202 quad_perm:[0,2,0,2] row_mask:0xf bank_mask:0xf
	v_mov_b32_dpp v215, v203 quad_perm:[0,2,0,2] row_mask:0xf bank_mask:0xf
	v_mov_b32_dpp v216, v202 quad_perm:[1,3,1,3] row_mask:0xf bank_mask:0xf
	v_mov_b32_dpp v217, v203 quad_perm:[1,3,1,3] row_mask:0xf bank_mask:0xf
	v_cndmask_b32_dpp v214, v204, v214, vcc quad_perm:[0,2,0,2] row_mask:0xf bank_mask:0xf
	v_cndmask_b32_dpp v215, v205, v215, vcc quad_perm:[0,2,0,2] row_mask:0xf bank_mask:0xf
	v_cndmask_b32_dpp v216, v204, v216, vcc quad_perm:[1,3,1,3] row_mask:0xf bank_mask:0xf
	v_cndmask_b32_dpp v217, v205, v217, vcc quad_perm:[1,3,1,3] row_mask:0xf bank_mask:0xf
	global_store_dwordx4 v[248:249], v[214:217], off offset:0
	v_pk_mul_f32 v[198:199], v[42:43], v[192:193] op_sel_hi:[1,0]
	v_pk_fma_f32 v[198:199], v[198:199], v[142:143], v[158:159]
	v_pk_mul_f32 v[200:201], v[44:45], v[192:193] op_sel_hi:[1,0]
	v_pk_fma_f32 v[200:201], v[200:201], v[144:145], v[160:161]
	v_cvt_pk_bf16_f32 v202, v198, v199
	v_cvt_pk_bf16_f32 v203, v200, v201
	v_pk_mul_f32 v[198:199], v[38:39], v[192:193] op_sel_hi:[1,0]
	v_pk_fma_f32 v[198:199], v[198:199], v[146:147], v[162:163]
	v_pk_mul_f32 v[200:201], v[40:41], v[192:193] op_sel_hi:[1,0]
	v_pk_fma_f32 v[200:201], v[200:201], v[148:149], v[164:165]
	v_cvt_pk_bf16_f32 v204, v198, v199
	v_cvt_pk_bf16_f32 v205, v200, v201
	v_mov_b32_dpp v214, v202 quad_perm:[0,2,0,2] row_mask:0xf bank_mask:0xf
	v_mov_b32_dpp v215, v203 quad_perm:[0,2,0,2] row_mask:0xf bank_mask:0xf
	v_mov_b32_dpp v216, v202 quad_perm:[1,3,1,3] row_mask:0xf bank_mask:0xf
	v_mov_b32_dpp v217, v203 quad_perm:[1,3,1,3] row_mask:0xf bank_mask:0xf
	v_cndmask_b32_dpp v214, v204, v214, vcc quad_perm:[0,2,0,2] row_mask:0xf bank_mask:0xf
	v_cndmask_b32_dpp v215, v205, v215, vcc quad_perm:[0,2,0,2] row_mask:0xf bank_mask:0xf
	v_cndmask_b32_dpp v216, v204, v216, vcc quad_perm:[1,3,1,3] row_mask:0xf bank_mask:0xf
	v_cndmask_b32_dpp v217, v205, v217, vcc quad_perm:[1,3,1,3] row_mask:0xf bank_mask:0xf
	global_store_dwordx4 v[248:249], v[214:217], off offset:256
	s_mov_b32 s30, 0x50000
	v_lshl_add_u64 v[248:249], v[244:245], 0, s[30:31]
	v_pk_mul_f32 v[198:199], v[34:35], v[194:195] op_sel_hi:[1,0]
	v_pk_fma_f32 v[198:199], v[198:199], v[134:135], v[150:151]
	v_pk_mul_f32 v[200:201], v[36:37], v[194:195] op_sel_hi:[1,0]
	v_pk_fma_f32 v[200:201], v[200:201], v[136:137], v[152:153]
	v_cvt_pk_bf16_f32 v202, v198, v199
	v_cvt_pk_bf16_f32 v203, v200, v201
	v_pk_mul_f32 v[198:199], v[30:31], v[194:195] op_sel_hi:[1,0]
	v_pk_fma_f32 v[198:199], v[198:199], v[138:139], v[154:155]
	v_pk_mul_f32 v[200:201], v[32:33], v[194:195] op_sel_hi:[1,0]
	v_pk_fma_f32 v[200:201], v[200:201], v[140:141], v[156:157]
	v_cvt_pk_bf16_f32 v204, v198, v199
	v_cvt_pk_bf16_f32 v205, v200, v201
	v_mov_b32_dpp v214, v202 quad_perm:[0,2,0,2] row_mask:0xf bank_mask:0xf
	v_mov_b32_dpp v215, v203 quad_perm:[0,2,0,2] row_mask:0xf bank_mask:0xf
	v_mov_b32_dpp v216, v202 quad_perm:[1,3,1,3] row_mask:0xf bank_mask:0xf
	v_mov_b32_dpp v217, v203 quad_perm:[1,3,1,3] row_mask:0xf bank_mask:0xf
	v_cndmask_b32_dpp v214, v204, v214, vcc quad_perm:[0,2,0,2] row_mask:0xf bank_mask:0xf
	v_cndmask_b32_dpp v215, v205, v215, vcc quad_perm:[0,2,0,2] row_mask:0xf bank_mask:0xf
	v_cndmask_b32_dpp v216, v204, v216, vcc quad_perm:[1,3,1,3] row_mask:0xf bank_mask:0xf
	v_cndmask_b32_dpp v217, v205, v217, vcc quad_perm:[1,3,1,3] row_mask:0xf bank_mask:0xf
	global_store_dwordx4 v[248:249], v[214:217], off offset:0
	v_pk_mul_f32 v[198:199], v[26:27], v[194:195] op_sel_hi:[1,0]
	v_pk_fma_f32 v[198:199], v[198:199], v[142:143], v[158:159]
	v_pk_mul_f32 v[200:201], v[28:29], v[194:195] op_sel_hi:[1,0]
	v_pk_fma_f32 v[200:201], v[200:201], v[144:145], v[160:161]
	v_cvt_pk_bf16_f32 v202, v198, v199
	v_cvt_pk_bf16_f32 v203, v200, v201
	v_pk_mul_f32 v[198:199], v[22:23], v[194:195] op_sel_hi:[1,0]
	v_pk_fma_f32 v[198:199], v[198:199], v[146:147], v[162:163]
	v_pk_mul_f32 v[200:201], v[24:25], v[194:195] op_sel_hi:[1,0]
	v_pk_fma_f32 v[200:201], v[200:201], v[148:149], v[164:165]
	v_cvt_pk_bf16_f32 v204, v198, v199
	v_cvt_pk_bf16_f32 v205, v200, v201
	v_mov_b32_dpp v214, v202 quad_perm:[0,2,0,2] row_mask:0xf bank_mask:0xf
	v_mov_b32_dpp v215, v203 quad_perm:[0,2,0,2] row_mask:0xf bank_mask:0xf
	v_mov_b32_dpp v216, v202 quad_perm:[1,3,1,3] row_mask:0xf bank_mask:0xf
	v_mov_b32_dpp v217, v203 quad_perm:[1,3,1,3] row_mask:0xf bank_mask:0xf
	v_cndmask_b32_dpp v214, v204, v214, vcc quad_perm:[0,2,0,2] row_mask:0xf bank_mask:0xf
	v_cndmask_b32_dpp v215, v205, v215, vcc quad_perm:[0,2,0,2] row_mask:0xf bank_mask:0xf
	v_cndmask_b32_dpp v216, v204, v216, vcc quad_perm:[1,3,1,3] row_mask:0xf bank_mask:0xf
	v_cndmask_b32_dpp v217, v205, v217, vcc quad_perm:[1,3,1,3] row_mask:0xf bank_mask:0xf
	global_store_dwordx4 v[248:249], v[214:217], off offset:256
	s_mov_b32 s30, 0x58000
	v_lshl_add_u64 v[248:249], v[244:245], 0, s[30:31]
	v_pk_mul_f32 v[198:199], v[18:19], v[196:197] op_sel_hi:[1,0]
	v_pk_fma_f32 v[198:199], v[198:199], v[134:135], v[150:151]
	v_pk_mul_f32 v[200:201], v[20:21], v[196:197] op_sel_hi:[1,0]
	v_pk_fma_f32 v[200:201], v[200:201], v[136:137], v[152:153]
	v_cvt_pk_bf16_f32 v202, v198, v199
	v_cvt_pk_bf16_f32 v203, v200, v201
	v_pk_mul_f32 v[198:199], v[14:15], v[196:197] op_sel_hi:[1,0]
	v_pk_fma_f32 v[198:199], v[198:199], v[138:139], v[154:155]
	v_pk_mul_f32 v[200:201], v[16:17], v[196:197] op_sel_hi:[1,0]
	v_pk_fma_f32 v[200:201], v[200:201], v[140:141], v[156:157]
	v_cvt_pk_bf16_f32 v204, v198, v199
	v_cvt_pk_bf16_f32 v205, v200, v201
	v_mov_b32_dpp v214, v202 quad_perm:[0,2,0,2] row_mask:0xf bank_mask:0xf
	v_mov_b32_dpp v215, v203 quad_perm:[0,2,0,2] row_mask:0xf bank_mask:0xf
	v_mov_b32_dpp v216, v202 quad_perm:[1,3,1,3] row_mask:0xf bank_mask:0xf
	v_mov_b32_dpp v217, v203 quad_perm:[1,3,1,3] row_mask:0xf bank_mask:0xf
	v_cndmask_b32_dpp v214, v204, v214, vcc quad_perm:[0,2,0,2] row_mask:0xf bank_mask:0xf
	v_cndmask_b32_dpp v215, v205, v215, vcc quad_perm:[0,2,0,2] row_mask:0xf bank_mask:0xf
	v_cndmask_b32_dpp v216, v204, v216, vcc quad_perm:[1,3,1,3] row_mask:0xf bank_mask:0xf
	v_cndmask_b32_dpp v217, v205, v217, vcc quad_perm:[1,3,1,3] row_mask:0xf bank_mask:0xf
	global_store_dwordx4 v[248:249], v[214:217], off offset:0
	v_pk_mul_f32 v[198:199], v[10:11], v[196:197] op_sel_hi:[1,0]
	v_pk_fma_f32 v[198:199], v[198:199], v[142:143], v[158:159]
	v_pk_mul_f32 v[200:201], v[12:13], v[196:197] op_sel_hi:[1,0]
	v_pk_fma_f32 v[200:201], v[200:201], v[144:145], v[160:161]
	v_cvt_pk_bf16_f32 v202, v198, v199
	v_cvt_pk_bf16_f32 v203, v200, v201
	v_pk_mul_f32 v[198:199], v[6:7], v[196:197] op_sel_hi:[1,0]
	v_pk_fma_f32 v[198:199], v[198:199], v[146:147], v[162:163]
	v_pk_mul_f32 v[200:201], v[8:9], v[196:197] op_sel_hi:[1,0]
	v_pk_fma_f32 v[200:201], v[200:201], v[148:149], v[164:165]
	v_cvt_pk_bf16_f32 v204, v198, v199
	v_cvt_pk_bf16_f32 v205, v200, v201
	v_mov_b32_dpp v214, v202 quad_perm:[0,2,0,2] row_mask:0xf bank_mask:0xf
	v_mov_b32_dpp v215, v203 quad_perm:[0,2,0,2] row_mask:0xf bank_mask:0xf
	v_mov_b32_dpp v216, v202 quad_perm:[1,3,1,3] row_mask:0xf bank_mask:0xf
	v_mov_b32_dpp v217, v203 quad_perm:[1,3,1,3] row_mask:0xf bank_mask:0xf
	v_cndmask_b32_dpp v214, v204, v214, vcc quad_perm:[0,2,0,2] row_mask:0xf bank_mask:0xf
	v_cndmask_b32_dpp v215, v205, v215, vcc quad_perm:[0,2,0,2] row_mask:0xf bank_mask:0xf
	v_cndmask_b32_dpp v216, v204, v216, vcc quad_perm:[1,3,1,3] row_mask:0xf bank_mask:0xf
	v_cndmask_b32_dpp v217, v205, v217, vcc quad_perm:[1,3,1,3] row_mask:0xf bank_mask:0xf
	global_store_dwordx4 v[248:249], v[214:217], off offset:256
	s_branch .Lrn_out_done
